# speedup vs baseline: 1.0131x; 1.0072x over previous
; #define WAIT_V(n) asm volatile("s_waitcnt vmcnt(" #n ")":::"memory")
; #define BAR __builtin_amdgcn_s_barrier()
; DEVINL void gemm8_mainloop(const u16* A, long lda, const u16* Bt, long ldb, int K, int brow, int bcol, f32x4 (&acc)[2][2][4][2], char* smem, int tid) {
;     ...
;   if(wr==1)BAR;
;   WAIT_V(4); BAR;
; DEVINL void compute_rs(const float* part, int m0, float* rs_s, int tid) {
;     ...
;   if (!half) rs_s[row] = rsqrtf(s * (1.f / 2048.f) + EPSN);
;   __syncthreads();
.LBB0_266:
	s_or_b64 exec, exec, s[2:3]
	v_readfirstlane_b32 s44, v167
	s_ashr_i32 s45, s44, 8
	s_cmp_lg_u32 s45, 1
	s_waitcnt lgkmcnt(0)
	s_barrier
	s_setprio 1
	s_cbranch_scc1 .LBB0_268
	s_setprio 0
	s_barrier

; #define WAIT_V(n) asm volatile("s_waitcnt vmcnt(" #n ")":::"memory")
; #define BAR __builtin_amdgcn_s_barrier()
; DEVINL void gemm8_mainloop(const u16* A, long lda, const u16* Bt, long ldb, int K, int brow, int bcol, f32x4 (&acc)[2][2][4][2], char* smem, int tid) {
;     ...
;   if(wr==1)BAR;
;   WAIT_V(4); BAR;
.LBB0_846:
	v_mov_b32_e32 v151, v176
	s_nop 0
	v_readfirstlane_b32 s31, v151
	s_ashr_i32 s0, s31, 8
	s_cmp_lg_u32 s0, 1
	s_setprio 1
	s_cbranch_scc1 .LBB0_848
	s_setprio 0
	s_barrier

; #define WAIT_V(n) asm volatile("s_waitcnt vmcnt(" #n ")":::"memory")
; #define BAR __builtin_amdgcn_s_barrier()
; DEVINL void gemm8_mainloop(const u16* A, long lda, const u16* Bt, long ldb, int K, int brow, int bcol, f32x4 (&acc)[2][2][4][2], char* smem, int tid) {
;     ...
;   if(wr==1)BAR;
;   WAIT_V(4); BAR;
; DEVINL void compute_rs(const float* part, int m0, float* rs_s, int tid) {
;     ...
;   if (!half) rs_s[row] = rsqrtf(s * (1.f / 2048.f) + EPSN);
;   __syncthreads();
.LBB0_913:
	s_or_b64 exec, exec, s[26:27]
	v_readfirstlane_b32 s0, v153
	s_ashr_i32 s1, s0, 8
	s_cmp_lg_u32 s1, 1
	s_waitcnt lgkmcnt(0)
	s_barrier
	s_setprio 1
	s_cbranch_scc1 .LBB0_915
	s_setprio 0
	s_barrier

; #define WAIT_V(n) asm volatile("s_waitcnt vmcnt(" #n ")":::"memory")
; #define BAR __builtin_amdgcn_s_barrier()
; DEVINL void gemm8_mainloop(const u16* A, long lda, const u16* Bt, long ldb, int K, int brow, int bcol, f32x4 (&acc)[2][2][4][2], char* smem, int tid) {
;     ...
;   if(wr==1)BAR;
;   WAIT_V(4); BAR;
.LBB0_962:
	v_mov_b32_e32 v151, v176
	s_nop 0
	v_readfirstlane_b32 s29, v151
	s_ashr_i32 s0, s29, 8
	s_cmp_lg_u32 s0, 1
	s_setprio 1
	s_cbranch_scc1 .LBB0_964
	s_setprio 0
	s_barrier

; #define WAIT_V(n) asm volatile("s_waitcnt vmcnt(" #n ")":::"memory")
; #define BAR __builtin_amdgcn_s_barrier()
; DEVINL void gemm8_mainloop(const u16* A, long lda, const u16* Bt, long ldb, int K, int brow, int bcol, f32x4 (&acc)[2][2][4][2], char* smem, int tid) {
;     ...
;   if(wr==1)BAR;
;   WAIT_V(4); BAR;
; DEVINL void compute_rs(const float* part, int m0, float* rs_s, int tid) {
;     ...
;   if (!half) rs_s[row] = rsqrtf(s * (1.f / 2048.f) + EPSN);
;   __syncthreads();
.LBB0_1289:
	s_or_b64 exec, exec, s[4:5]
	v_readfirstlane_b32 s0, v167
	s_ashr_i32 s1, s0, 8
	s_cmp_lg_u32 s1, 1
	s_waitcnt lgkmcnt(0)
	s_barrier
	s_setprio 1
	s_cbranch_scc1 .LBB0_1291
	s_setprio 0
	s_barrier

; #define WAIT_V(n) asm volatile("s_waitcnt vmcnt(" #n ")":::"memory")
; #define BAR __builtin_amdgcn_s_barrier()
; DEVINL void gemm8_mainloop(const u16* A, long lda, const u16* Bt, long ldb, int K, int brow, int bcol, f32x4 (&acc)[2][2][4][2], char* smem, int tid) {
;     ...
;   if(wr==1)BAR;
;   WAIT_V(4); BAR;
.LBB0_1868:
	v_mov_b32_e32 v151, v176
	s_nop 0
	v_readfirstlane_b32 s29, v151
	s_ashr_i32 s37, s29, 8
	s_cmp_lg_u32 s37, 1
	s_setprio 1
	s_cbranch_scc1 .LBB0_1870
	s_setprio 0
	s_barrier

; #define WAIT_V(n) asm volatile("s_waitcnt vmcnt(" #n ")":::"memory")
; #define BAR __builtin_amdgcn_s_barrier()
; DEVINL void gemm8_mainloop(const u16* A, long lda, const u16* Bt, long ldb, int K, int brow, int bcol, f32x4 (&acc)[2][2][4][2], char* smem, int tid) {
;     ...
;   if(wr==1)BAR;
;   WAIT_V(4); BAR;
; DEVINL void compute_rs(const float* part, int m0, float* rs_s, int tid) {
;     ...
;   if (!half) rs_s[row] = rsqrtf(s * (1.f / 2048.f) + EPSN);
;   __syncthreads();
.LBB0_1935:
	s_or_b64 exec, exec, s[24:25]
	v_readfirstlane_b32 s37, v153
	s_ashr_i32 s38, s37, 8
	s_cmp_lg_u32 s38, 1
	s_waitcnt lgkmcnt(0)
	s_barrier
	s_setprio 1
	s_cbranch_scc1 .LBB0_1937
	s_setprio 0
	s_barrier

; #define WAIT_V(n) asm volatile("s_waitcnt vmcnt(" #n ")":::"memory")
; #define BAR __builtin_amdgcn_s_barrier()
; DEVINL void gemm8_mainloop(const u16* A, long lda, const u16* Bt, long ldb, int K, int brow, int bcol, f32x4 (&acc)[2][2][4][2], char* smem, int tid) {
;     ...
;   if(wr==1)BAR;
;   WAIT_V(4); BAR;
.LBB0_1984:
	v_mov_b32_e32 v151, v176
	s_nop 0
	v_readfirstlane_b32 s27, v151
	s_ashr_i32 s34, s27, 8
	s_cmp_lg_u32 s34, 1
	s_setprio 1
	s_cbranch_scc1 .LBB0_1986
	s_setprio 0
	s_barrier
